# G sample-row split-K: all 48 fragment loads of both tasks in flight (shared A fragments); store-drain waits dropped at B and G tail entry
# speedup vs baseline: 1.0082x; 1.0055x over previous
; __device__ __forceinline__ int lane_fresh() { int l; asm volatile("v_mbcnt_lo_u32_b32 %0, -1, 0\n\tv_mbcnt_hi_u32_b32 %0, -1, %0" : "=v"(l)); return l; }
; #define MFMA16(a, b, c) __builtin_amdgcn_mfma_f32_16x16x32_bf16((a), (b), (c), 0, 0, 0)
; template <int NT, class FA, class FB, class FL>
; __device__ __forceinline__ void skgemm(FA aptr, FB bptr, FL ldf, const int KS, const int wv) {
;   float* part = (float*)g_shm;
;   const int lane = lane_fresh(), fr = lane & 15, fq = lane >> 4;
;   __syncthreads();
; #pragma unroll
;   for (int i = 0; i < NT; ++i) {
;     f32x4 acc = {0.f, 0.f, 0.f, 0.f};
;     const int ld = ldf(i);
;     const u16* ap = aptr(i) + (size_t)fr * ld + wv * KS + fq * 8;
;     const u16* bp = bptr(i) + (size_t)fr * ld + wv * KS + fq * 8;
; #pragma unroll 8
;     for (int k = 0; k < KS; k += 32) acc = MFMA16(*(const bf16x8*)(bp + k), *(const bf16x8*)(ap + k), acc);
;     *(f32x4*)(part + ((i * 8 + wv) * 64 + lane) * 4) = acc;
;   }
;   __syncthreads();
; __device__ __forceinline__ void phaseB(const Params& p, const int wv, const int rep) {
;     ...
;   for (int gb = blockIdx.x; gb < 256; gb += gridDim.x) {
;     const int task0 = gb * 14, mt = task0 / 448, nt0 = task0 - mt * 448;
;     const u16* Ab = XN + (size_t)(TP + mt * 16) * 1024;
;     const u16* Bb = (const u16*)(ws + OFF_WIN) + (size_t)(nt0 * 16) * 1024;
;     skgemm<14>([&](int) { return Ab; }, [&](int i) { return Bb + (size_t)i * 16 * 1024; }, [&](int) { return 1024; }, 128, wv);
.LBB0_225:
	s_ashr_i32 s23, s43, 31
	s_lshr_b32 s23, s23, 27
	s_add_i32 s23, s43, s23
	s_ashr_i32 s26, s23, 5
	s_mul_i32 s22, s43, 14
	s_mul_i32 s23, s26, 0xfffffe40
	s_add_i32 s27, s23, s22
	s_lshl_b32 s22, s26, 4
	s_addk_i32 s22, 0x4000
	s_ashr_i32 s23, s22, 31
	s_lshl_b64 s[24:25], s[22:23], 11
	s_add_u32 s24, s48, s24
	s_addc_u32 s25, s49, s25
	s_lshl_b32 s28, s27, 4
	s_ashr_i32 s29, s28, 31
	v_mbcnt_lo_u32_b32 v56, -1, 0
	v_mbcnt_hi_u32_b32 v56, -1, v56
	s_lshl_b64 s[28:29], s[28:29], 11
	v_ashrrev_i32_e32 v0, 1, v56
	v_lshlrev_b32_e32 v2, 11, v56
	v_and_b32_e32 v0, -8, v0
	v_and_b32_e32 v52, 0x7800, v2
	s_add_u32 s28, s50, s28
	v_ashrrev_i32_e32 v1, 31, v0
	v_lshl_add_u64 v[2:3], s[24:25], 0, v[52:53]
	s_addc_u32 s29, s51, s29
	v_lshl_add_u64 v[2:3], v[2:3], 0, s[0:1]
	v_lshlrev_b64 v[0:1], 1, v[0:1]
	v_lshl_add_u64 v[86:87], v[2:3], 0, v[0:1]
	v_lshl_add_u64 v[2:3], s[28:29], 0, v[52:53]
	v_lshl_add_u64 v[2:3], v[2:3], 0, s[0:1]
	v_lshl_add_u64 v[54:55], v[2:3], 0, v[0:1]
	s_mov_b32 s23, 0x8000
	v_add_co_u32_e32 v8, vcc, s23, v54
	s_mov_b32 s23, 0x10000
	s_nop 0
	v_addc_co_u32_e32 v9, vcc, 0, v55, vcc
	s_waitcnt lgkmcnt(0)
	s_barrier
	global_load_dwordx4 v[4:7], v[54:55], off
	global_load_dwordx4 v[0:3], v[86:87], off
	global_load_dwordx4 v[12:15], v[8:9], off
	v_add_co_u32_e32 v8, vcc, s23, v54
	s_mov_b32 s23, 0x18000
	s_nop 0
	v_addc_co_u32_e32 v9, vcc, 0, v55, vcc
	global_load_dwordx4 v[16:19], v[8:9], off
	v_add_co_u32_e32 v8, vcc, s23, v54
	s_mov_b32 s27, 0x20000
	s_nop 0
	v_addc_co_u32_e32 v9, vcc, 0, v55, vcc
	s_mov_b64 s[24:25], 0x8000
	global_load_dwordx4 v[20:23], v[8:9], off
	v_add_co_u32_e32 v8, vcc, s27, v54
	v_lshl_add_u64 v[78:79], v[54:55], 0, s[24:25]
	s_nop 0
	v_addc_co_u32_e32 v9, vcc, 0, v55, vcc
	global_load_dwordx4 v[24:27], v[8:9], off
	global_load_dwordx4 v[28:31], v[54:55], off offset:64
	s_nop 0
	global_load_dwordx4 v[8:11], v[86:87], off offset:64
	global_load_dwordx4 v[32:35], v[78:79], off offset:64
	global_load_dwordx4 v[40:43], v[78:79], off offset:192
	s_mov_b64 s[28:29], 0x10000
	v_lshl_add_u64 v[82:83], v[54:55], 0, s[28:29]
	global_load_dwordx4 v[36:39], v[82:83], off offset:64
	global_load_dwordx4 v[58:61], v[82:83], off offset:192
	s_mov_b64 s[30:31], 0x18000
	v_lshl_add_u64 v[88:89], v[54:55], 0, s[30:31]
	global_load_dwordx4 v[48:51], v[88:89], off offset:64
	s_mov_b64 s[24:25], 0x20000
	v_lshl_add_u64 v[90:91], v[54:55], 0, s[24:25]
	global_load_dwordx4 v[62:65], v[90:91], off offset:64
	global_load_dwordx4 v[66:69], v[88:89], off offset:192
	s_mov_b32 s23, 0x28000
	s_mov_b64 s[24:25], 0x28000
	v_lshlrev_b32_e32 v52, 4, v56
	v_add_u32_e32 v102, s13, v52
	s_waitcnt vmcnt(13)
	v_mfma_f32_16x16x32_bf16 v[4:7], v[4:7], v[0:3], 0
	s_waitcnt vmcnt(12)
	v_mfma_f32_16x16x32_bf16 v[44:47], v[12:15], v[0:3], 0
	global_load_dwordx4 v[70:73], v[54:55], off offset:128
	global_load_dwordx4 v[12:15], v[86:87], off offset:128
	global_load_dwordx4 v[74:77], v[90:91], off offset:192
	s_nop 0
	global_load_dwordx4 v[78:81], v[78:79], off offset:128
	s_waitcnt vmcnt(10)
	v_mfma_f32_16x16x32_bf16 v[32:35], v[32:35], v[8:11], v[44:47]
	s_nop 2
	global_load_dwordx4 v[44:47], v[88:89], off offset:128
	s_nop 0
	global_load_dwordx4 v[82:85], v[82:83], off offset:128
	v_mfma_f32_16x16x32_bf16 v[16:19], v[16:19], v[0:3], 0
	v_mfma_f32_16x16x32_bf16 v[28:31], v[28:31], v[8:11], v[4:7]
	s_nop 2
	global_load_dwordx4 v[4:7], v[86:87], off offset:192
	v_mfma_f32_16x16x32_bf16 v[20:23], v[20:23], v[0:3], 0
	s_waitcnt vmcnt(11)
	v_mfma_f32_16x16x32_bf16 v[16:19], v[36:39], v[8:11], v[16:19]
	global_load_dwordx4 v[36:39], v[90:91], off offset:128
	s_waitcnt vmcnt(10)
	v_mfma_f32_16x16x32_bf16 v[20:23], v[48:51], v[8:11], v[20:23]
	global_load_dwordx4 v[48:51], v[54:55], off offset:192
	v_mfma_f32_16x16x32_bf16 v[24:27], v[24:27], v[0:3], 0
	s_waitcnt vmcnt(10)
	v_mfma_f32_16x16x32_bf16 v[24:27], v[62:65], v[8:11], v[24:27]
	s_waitcnt vmcnt(7)
	v_mfma_f32_16x16x32_bf16 v[28:31], v[70:73], v[12:15], v[28:31]
	s_waitcnt vmcnt(5)
	v_mfma_f32_16x16x32_bf16 v[32:35], v[78:81], v[12:15], v[32:35]
	s_waitcnt vmcnt(4)
	v_mfma_f32_16x16x32_bf16 v[44:47], v[44:47], v[12:15], v[20:23]
	s_waitcnt vmcnt(2)
	v_mfma_f32_16x16x32_bf16 v[20:23], v[40:43], v[4:7], v[32:35]
	s_nop 3
	v_add_co_u32_e32 v32, vcc, s23, v54
	s_mov_b32 s23, 0x30000
	s_nop 0
	v_addc_co_u32_e32 v33, vcc, 0, v55, vcc
	global_load_dwordx4 v[40:43], v[32:33], off
	s_waitcnt vmcnt(2)
	v_mfma_f32_16x16x32_bf16 v[36:39], v[36:39], v[12:15], v[24:27]
	v_mfma_f32_16x16x32_bf16 v[62:65], v[82:85], v[12:15], v[16:19]
	s_waitcnt vmcnt(1)
	v_mfma_f32_16x16x32_bf16 v[16:19], v[48:51], v[4:7], v[28:31]
	v_lshl_add_u64 v[48:49], v[54:55], 0, s[24:25]
	s_mov_b64 s[24:25], 0x30000
	v_mfma_f32_16x16x32_bf16 v[28:31], v[66:69], v[4:7], v[44:47]
	v_mfma_f32_16x16x32_bf16 v[32:35], v[74:77], v[4:7], v[36:39]
	s_nop 2
	global_load_dwordx4 v[36:39], v[48:49], off offset:64
	global_load_dwordx4 v[44:47], v[48:49], off offset:192
	s_nop 0
	global_load_dwordx4 v[48:51], v[48:49], off offset:128
	v_mfma_f32_16x16x32_bf16 v[24:27], v[58:61], v[4:7], v[62:65]
	v_lshl_add_u64 v[58:59], v[54:55], 0, s[24:25]
	s_mov_b64 s[24:25], 0x38000
	s_nop 0
	v_lshl_add_u64 v[62:63], v[54:55], 0, s[24:25]
	s_mov_b64 s[24:25], 0x40000
	v_lshl_add_u64 v[66:67], v[54:55], 0, s[24:25]
	s_mov_b64 s[24:25], 0x48000
	v_lshl_add_u64 v[70:71], v[54:55], 0, s[24:25]
	s_mov_b64 s[24:25], 0x50000
	v_lshl_add_u64 v[74:75], v[54:55], 0, s[24:25]
	s_mov_b64 s[24:25], 0x58000
	s_waitcnt vmcnt(3)
	v_mfma_f32_16x16x32_bf16 v[40:43], v[40:43], v[0:3], 0
	v_lshl_add_u64 v[78:79], v[54:55], 0, s[24:25]
	s_mov_b64 s[24:25], 0x60000
	v_lshl_add_u64 v[90:91], v[54:55], 0, s[24:25]
	s_waitcnt vmcnt(2)
; #define MFMA16(a, b, c) __builtin_amdgcn_mfma_f32_16x16x32_bf16((a), (b), (c), 0, 0, 0)
; template <int NT, class FA, class FB, class FL>
; __device__ __forceinline__ void skgemm(FA aptr, FB bptr, FL ldf, const int KS, const int wv) {
;     ...
;   for (int i = 0; i < NT; ++i) {
;     f32x4 acc = {0.f, 0.f, 0.f, 0.f};
;     const int ld = ldf(i);
;     const u16* ap = aptr(i) + (size_t)fr * ld + wv * KS + fq * 8;
;     const u16* bp = bptr(i) + (size_t)fr * ld + wv * KS + fq * 8;
; #pragma unroll 8
;     for (int k = 0; k < KS; k += 32) acc = MFMA16(*(const bf16x8*)(bp + k), *(const bf16x8*)(ap + k), acc);
;     *(f32x4*)(part + ((i * 8 + wv) * 64 + lane) * 4) = acc;
;   }
;   __syncthreads();
	v_mfma_f32_16x16x32_bf16 v[36:39], v[36:39], v[8:11], v[40:43]
	s_nop 2
	v_add_co_u32_e32 v40, vcc, s23, v54
	s_mov_b32 s23, 0x38000
	s_nop 0
	v_addc_co_u32_e32 v41, vcc, 0, v55, vcc
	global_load_dwordx4 v[40:43], v[40:41], off
	s_waitcnt vmcnt(1)
	v_mfma_f32_16x16x32_bf16 v[36:39], v[48:51], v[12:15], v[36:39]
	s_mov_b64 s[24:25], 0x68000
	v_mfma_f32_16x16x32_bf16 v[36:39], v[44:47], v[4:7], v[36:39]
	global_load_dwordx4 v[44:47], v[58:59], off offset:64
	global_load_dwordx4 v[48:51], v[58:59], off offset:192
	s_nop 0
	global_load_dwordx4 v[58:61], v[58:59], off offset:128
	s_waitcnt vmcnt(3)
	v_mfma_f32_16x16x32_bf16 v[40:43], v[40:43], v[0:3], 0
	s_waitcnt vmcnt(2)
	v_mfma_f32_16x16x32_bf16 v[40:43], v[44:47], v[8:11], v[40:43]
	v_add_co_u32_e32 v44, vcc, s23, v54
	s_mov_b32 s23, 0x40000
	s_nop 0
	v_addc_co_u32_e32 v45, vcc, 0, v55, vcc
	global_load_dwordx4 v[44:47], v[44:45], off
	s_waitcnt vmcnt(1)
	v_mfma_f32_16x16x32_bf16 v[40:43], v[58:61], v[12:15], v[40:43]
	v_mfma_f32_16x16x32_bf16 v[40:43], v[48:51], v[4:7], v[40:43]
	global_load_dwordx4 v[48:51], v[62:63], off offset:64
	global_load_dwordx4 v[58:61], v[62:63], off offset:192
	s_nop 0
	global_load_dwordx4 v[62:65], v[62:63], off offset:128
	s_waitcnt vmcnt(3)
	v_mfma_f32_16x16x32_bf16 v[44:47], v[44:47], v[0:3], 0
	s_waitcnt vmcnt(2)
	v_mfma_f32_16x16x32_bf16 v[44:47], v[48:51], v[8:11], v[44:47]
	v_add_co_u32_e32 v48, vcc, s23, v54
	s_mov_b32 s23, 0x48000
	s_nop 0
	v_addc_co_u32_e32 v49, vcc, 0, v55, vcc
	global_load_dwordx4 v[48:51], v[48:49], off
	s_waitcnt vmcnt(1)
	v_mfma_f32_16x16x32_bf16 v[44:47], v[62:65], v[12:15], v[44:47]
	v_mfma_f32_16x16x32_bf16 v[44:47], v[58:61], v[4:7], v[44:47]
	global_load_dwordx4 v[58:61], v[66:67], off offset:64
	global_load_dwordx4 v[62:65], v[66:67], off offset:192
	s_nop 0
	global_load_dwordx4 v[66:69], v[66:67], off offset:128
	s_waitcnt vmcnt(3)
	v_mfma_f32_16x16x32_bf16 v[48:51], v[48:51], v[0:3], 0
	s_waitcnt vmcnt(2)
	v_mfma_f32_16x16x32_bf16 v[48:51], v[58:61], v[8:11], v[48:51]
	v_add_co_u32_e32 v58, vcc, s23, v54
	s_mov_b32 s23, 0x50000
	s_nop 0
	v_addc_co_u32_e32 v59, vcc, 0, v55, vcc
	global_load_dwordx4 v[58:61], v[58:59], off
	s_waitcnt vmcnt(1)
	v_mfma_f32_16x16x32_bf16 v[48:51], v[66:69], v[12:15], v[48:51]
	v_mfma_f32_16x16x32_bf16 v[48:51], v[62:65], v[4:7], v[48:51]
	global_load_dwordx4 v[62:65], v[70:71], off offset:64
	global_load_dwordx4 v[66:69], v[70:71], off offset:192
	s_nop 0
	global_load_dwordx4 v[70:73], v[70:71], off offset:128
	s_waitcnt vmcnt(3)
	v_mfma_f32_16x16x32_bf16 v[58:61], v[58:61], v[0:3], 0
	s_waitcnt vmcnt(2)
	v_mfma_f32_16x16x32_bf16 v[58:61], v[62:65], v[8:11], v[58:61]
	v_add_co_u32_e32 v62, vcc, s23, v54
	s_mov_b32 s23, 0x58000
	s_nop 0
	v_addc_co_u32_e32 v63, vcc, 0, v55, vcc
	global_load_dwordx4 v[62:65], v[62:63], off
	s_waitcnt vmcnt(1)
	v_mfma_f32_16x16x32_bf16 v[58:61], v[70:73], v[12:15], v[58:61]
	v_mfma_f32_16x16x32_bf16 v[58:61], v[66:69], v[4:7], v[58:61]
	global_load_dwordx4 v[66:69], v[74:75], off offset:64
	global_load_dwordx4 v[70:73], v[74:75], off offset:192
	s_nop 0
	global_load_dwordx4 v[74:77], v[74:75], off offset:128
	s_waitcnt vmcnt(3)
	v_mfma_f32_16x16x32_bf16 v[62:65], v[62:65], v[0:3], 0
	s_waitcnt vmcnt(2)
	v_mfma_f32_16x16x32_bf16 v[62:65], v[66:69], v[8:11], v[62:65]
	v_add_co_u32_e32 v66, vcc, s23, v54
	s_mov_b32 s23, 0x60000
	s_nop 0
	v_addc_co_u32_e32 v67, vcc, 0, v55, vcc
	global_load_dwordx4 v[66:69], v[66:67], off
	s_waitcnt vmcnt(1)
	v_mfma_f32_16x16x32_bf16 v[62:65], v[74:77], v[12:15], v[62:65]
	global_load_dwordx4 v[74:77], v[78:79], off offset:64
	v_add_co_u32_e32 v82, vcc, s23, v54
	v_mfma_f32_16x16x32_bf16 v[62:65], v[70:73], v[4:7], v[62:65]
	global_load_dwordx4 v[70:73], v[78:79], off offset:128
	s_nop 0
	global_load_dwordx4 v[78:81], v[78:79], off offset:192
	v_addc_co_u32_e32 v83, vcc, 0, v55, vcc
	s_waitcnt vmcnt(3)
	v_mfma_f32_16x16x32_bf16 v[66:69], v[66:69], v[0:3], 0
	s_mov_b32 s23, 0x68000
	global_load_dwordx4 v[82:85], v[82:83], off
	s_waitcnt vmcnt(3)
	v_mfma_f32_16x16x32_bf16 v[66:69], v[74:77], v[8:11], v[66:69]
	global_load_dwordx4 v[74:77], v[90:91], off offset:64
	global_load_dwordx4 v[86:89], v[90:91], off offset:128
	s_waitcnt vmcnt(4)
	v_mfma_f32_16x16x32_bf16 v[66:69], v[70:73], v[12:15], v[66:69]
	global_load_dwordx4 v[70:73], v[90:91], off offset:192
	v_add_co_u32_e32 v90, vcc, s23, v54
	s_waitcnt vmcnt(4)
	v_mfma_f32_16x16x32_bf16 v[66:69], v[78:81], v[4:7], v[66:69]
	v_addc_co_u32_e32 v91, vcc, 0, v55, vcc
	global_load_dwordx4 v[90:93], v[90:91], off
	v_lshl_add_u64 v[54:55], v[54:55], 0, s[24:25]
	global_load_dwordx4 v[94:97], v[54:55], off offset:64
	global_load_dwordx4 v[78:81], v[54:55], off offset:128
	global_load_dwordx4 v[98:101], v[54:55], off offset:192
	s_waitcnt vmcnt(7)
	v_mfma_f32_16x16x32_bf16 v[82:85], v[82:85], v[0:3], 0
	ds_write_b128 v102, v[16:19]
	ds_write_b128 v102, v[20:23] offset:8192
	ds_write_b128 v102, v[24:27] offset:16384
	ds_write_b128 v102, v[28:31] offset:24576
	ds_write_b128 v102, v[32:35] offset:32768
	ds_write_b128 v102, v[36:39] offset:40960
	ds_write_b128 v102, v[40:43] offset:49152
	ds_write_b128 v102, v[44:47] offset:57344
	s_waitcnt vmcnt(3)
	v_mfma_f32_16x16x32_bf16 v[0:3], v[90:93], v[0:3], 0
	v_add_u32_e32 v20, s17, v52
	ds_write_b128 v20, v[48:51]
	v_add_u32_e32 v20, s19, v52
	v_mfma_f32_16x16x32_bf16 v[54:57], v[74:77], v[8:11], v[82:85]
	s_andn2_b64 vcc, exec, s[4:5]
	ds_write_b128 v20, v[58:61]
	s_waitcnt vmcnt(2)
	v_mfma_f32_16x16x32_bf16 v[0:3], v[94:97], v[8:11], v[0:3]
	v_add_u32_e32 v8, s21, v52
	ds_write_b128 v8, v[62:65]
	v_add_u32_e32 v8, s33, v52
	v_mfma_f32_16x16x32_bf16 v[16:19], v[86:89], v[12:15], v[54:57]
	ds_write_b128 v8, v[66:69]
	v_add_u32_e32 v8, s38, v52
	s_waitcnt vmcnt(1)
	v_mfma_f32_16x16x32_bf16 v[0:3], v[78:81], v[12:15], v[0:3]
	v_mfma_f32_16x16x32_bf16 v[16:19], v[70:73], v[4:7], v[16:19]
	s_waitcnt vmcnt(0)
	v_mfma_f32_16x16x32_bf16 v[0:3], v[98:101], v[4:7], v[0:3]
	v_add_u32_e32 v4, s39, v52
	s_nop 4
	ds_write_b128 v8, v[16:19]
	s_nop 0
	ds_write_b128 v4, v[0:3]
	s_waitcnt lgkmcnt(0)
	s_barrier
	s_cbranch_vccnz .LBB0_224
	s_ashr_i32 s23, s22, 11
	s_mul_hi_i32 s25, s23, 0x4800
	s_mulk_i32 s23, 0x4800
	s_add_u32 s24, s48, s23
	s_addc_u32 s25, s49, s25
	s_mul_i32 s23, s26, 0xffffe400
	s_mov_b32 s44, s15
	s_mov_b32 s45, s40
	s_branch .LBB0_229

; __device__ __forceinline__ int lane_fresh() { int l; asm volatile("v_mbcnt_lo_u32_b32 %0, -1, 0\n\tv_mbcnt_hi_u32_b32 %0, -1, %0" : "=v"(l)); return l; }
; #define MFMA16(a, b, c) __builtin_amdgcn_mfma_f32_16x16x32_bf16((a), (b), (c), 0, 0, 0)
; template <int NT, class FA, class FB, class FL>
; __device__ __forceinline__ void skgemm(FA aptr, FB bptr, FL ldf, const int KS, const int wv) {
;   float* part = (float*)g_shm;
;   const int lane = lane_fresh(), fr = lane & 15, fq = lane >> 4;
;   __syncthreads();
; #pragma unroll
;   for (int i = 0; i < NT; ++i) {
;     f32x4 acc = {0.f, 0.f, 0.f, 0.f};
;     const int ld = ldf(i);
;     const u16* ap = aptr(i) + (size_t)fr * ld + wv * KS + fq * 8;
;     const u16* bp = bptr(i) + (size_t)fr * ld + wv * KS + fq * 8;
; #pragma unroll 8
;     for (int k = 0; k < KS; k += 32) acc = MFMA16(*(const bf16x8*)(bp + k), *(const bf16x8*)(ap + k), acc);
;     *(f32x4*)(part + ((i * 8 + wv) * 64 + lane) * 4) = acc;
;   }
;   __syncthreads();
; __device__ __forceinline__ void phaseG(const Params& p, const int wv, const int rep, unsigned* bar, const bool fused) {
;     ...
;   for (int gb = blockIdx.x; gb < 256; gb += gridDim.x) {
;     const int task0 = gb * 2, mt = task0 >> 6, nt0 = task0 & 63;
;     const u16* Ab = ACT + (size_t)(TP + mt * 16) * 4096;
;     skgemm<2>([&](int) { return Ab; }, [&](int i) { return WDN + (size_t)((nt0 + i) * 16) * 4096; }, [&](int) { return 4096; }, 512, wv);
.LBB0_1183:
	s_mov_b32 s40, s19
	s_ashr_i32 s19, s19, 1
	s_and_b32 s22, s19, -16
	s_add_i32 s20, s22, 0x4000
	v_mbcnt_lo_u32_b32 v16, -1, 0
	v_mbcnt_hi_u32_b32 v16, -1, v16
	s_ashr_i32 s21, s20, 31
	v_ashrrev_i32_e32 v0, 1, v16
	v_and_b32_e32 v0, -8, v0
	v_lshlrev_b32_e32 v2, 13, v16
	s_lshl_b32 s2, s35, 17
	s_lshl_b64 s[24:25], s[20:21], 13
	v_ashrrev_i32_e32 v1, 31, v0
	v_and_b32_e32 v4, 0x1e000, v2
	s_and_b32 s2, s2, 0x7c0000
	v_or_b32_e32 v2, s24, v4
	v_mov_b32_e32 v3, s25
	v_lshlrev_b64 v[0:1], 1, v[0:1]
	v_lshl_add_u64 v[2:3], v[2:3], 0, v[0:1]
	v_or_b32_e32 v4, s2, v4
	v_lshl_add_u64 v[6:7], s[6:7], 0, v[2:3]
	v_lshl_add_u64 v[8:9], v[4:5], 0, v[0:1]
	v_lshl_add_u64 v[10:11], s[12:13], 0, v[8:9]
	s_movk_i32 s2, 0xffe0
	v_mov_b64_e32 v[12:13], v[6:7]
	v_mov_b32_e32 v0, 0
	v_mov_b32_e32 v1, v5
	v_mov_b32_e32 v2, v5
	v_mov_b32_e32 v3, v5
	s_barrier
	v_lshl_add_u64 v[8:9], s[14:15], 0, v[8:9]
	v_lshlrev_b32_e32 v4, 4, v16
	v_add_u32_e32 v4, s33, v4
	global_load_dwordx4 v[50:53], v[12:13], off offset:-256
	global_load_dwordx4 v[114:117], v[10:11], off offset:-256
	global_load_dwordx4 v[54:57], v[12:13], off offset:-192
	global_load_dwordx4 v[118:121], v[10:11], off offset:-192
	global_load_dwordx4 v[58:61], v[12:13], off offset:-128
	global_load_dwordx4 v[122:125], v[10:11], off offset:-128
	global_load_dwordx4 v[62:65], v[12:13], off offset:-64
	global_load_dwordx4 v[126:129], v[10:11], off offset:-64
	global_load_dwordx4 v[66:69], v[12:13], off
	global_load_dwordx4 v[130:133], v[10:11], off
	global_load_dwordx4 v[70:73], v[12:13], off offset:64
	global_load_dwordx4 v[134:137], v[10:11], off offset:64
	global_load_dwordx4 v[74:77], v[12:13], off offset:128
	global_load_dwordx4 v[138:141], v[10:11], off offset:128
	global_load_dwordx4 v[78:81], v[12:13], off offset:192
	global_load_dwordx4 v[142:145], v[10:11], off offset:192
	global_load_dwordx4 v[82:85], v[12:13], off offset:256
	global_load_dwordx4 v[146:149], v[10:11], off offset:256
	global_load_dwordx4 v[86:89], v[12:13], off offset:320
	global_load_dwordx4 v[150:153], v[10:11], off offset:320
	global_load_dwordx4 v[90:93], v[12:13], off offset:384
	global_load_dwordx4 v[154:157], v[10:11], off offset:384
	global_load_dwordx4 v[94:97], v[12:13], off offset:448
	global_load_dwordx4 v[158:161], v[10:11], off offset:448
	global_load_dwordx4 v[98:101], v[12:13], off offset:512
	global_load_dwordx4 v[162:165], v[10:11], off offset:512
	global_load_dwordx4 v[102:105], v[12:13], off offset:576
	global_load_dwordx4 v[166:169], v[10:11], off offset:576
	global_load_dwordx4 v[106:109], v[12:13], off offset:640
	global_load_dwordx4 v[170:173], v[10:11], off offset:640
	global_load_dwordx4 v[110:113], v[12:13], off offset:704
	global_load_dwordx4 v[174:177], v[10:11], off offset:704
	global_load_dwordx4 v[178:181], v[8:9], off offset:-256
	global_load_dwordx4 v[182:185], v[8:9], off offset:-192
	global_load_dwordx4 v[186:189], v[8:9], off offset:-128
	global_load_dwordx4 v[190:193], v[8:9], off offset:-64
	global_load_dwordx4 v[194:197], v[8:9], off
	global_load_dwordx4 v[198:201], v[8:9], off offset:64
	global_load_dwordx4 v[202:205], v[8:9], off offset:128
	global_load_dwordx4 v[206:209], v[8:9], off offset:192
	global_load_dwordx4 v[210:213], v[8:9], off offset:256
	global_load_dwordx4 v[214:217], v[8:9], off offset:320
	global_load_dwordx4 v[218:221], v[8:9], off offset:384
	global_load_dwordx4 v[222:225], v[8:9], off offset:448
	global_load_dwordx4 v[226:229], v[8:9], off offset:512
	global_load_dwordx4 v[230:233], v[8:9], off offset:576
	global_load_dwordx4 v[234:237], v[8:9], off offset:640
	global_load_dwordx4 v[238:241], v[8:9], off offset:704
	s_waitcnt vmcnt(46)
	v_mfma_f32_16x16x32_bf16 v[0:3], v[114:117], v[50:53], 0
	s_waitcnt vmcnt(44)
	v_mfma_f32_16x16x32_bf16 v[0:3], v[118:121], v[54:57], v[0:3]
	s_waitcnt vmcnt(42)
	v_mfma_f32_16x16x32_bf16 v[0:3], v[122:125], v[58:61], v[0:3]
	s_waitcnt vmcnt(40)
	v_mfma_f32_16x16x32_bf16 v[0:3], v[126:129], v[62:65], v[0:3]
	s_waitcnt vmcnt(38)
	v_mfma_f32_16x16x32_bf16 v[0:3], v[130:133], v[66:69], v[0:3]
	s_waitcnt vmcnt(36)
	v_mfma_f32_16x16x32_bf16 v[0:3], v[134:137], v[70:73], v[0:3]
	s_waitcnt vmcnt(34)
	v_mfma_f32_16x16x32_bf16 v[0:3], v[138:141], v[74:77], v[0:3]
	s_waitcnt vmcnt(32)
	v_mfma_f32_16x16x32_bf16 v[0:3], v[142:145], v[78:81], v[0:3]
	s_waitcnt vmcnt(30)
	v_mfma_f32_16x16x32_bf16 v[0:3], v[146:149], v[82:85], v[0:3]
	s_waitcnt vmcnt(28)
	v_mfma_f32_16x16x32_bf16 v[0:3], v[150:153], v[86:89], v[0:3]
	s_waitcnt vmcnt(26)
	v_mfma_f32_16x16x32_bf16 v[0:3], v[154:157], v[90:93], v[0:3]
	s_waitcnt vmcnt(24)
	v_mfma_f32_16x16x32_bf16 v[0:3], v[158:161], v[94:97], v[0:3]
	s_waitcnt vmcnt(22)
	v_mfma_f32_16x16x32_bf16 v[0:3], v[162:165], v[98:101], v[0:3]
	s_waitcnt vmcnt(20)
	v_mfma_f32_16x16x32_bf16 v[0:3], v[166:169], v[102:105], v[0:3]
	s_waitcnt vmcnt(18)
	v_mfma_f32_16x16x32_bf16 v[0:3], v[170:173], v[106:109], v[0:3]
	s_waitcnt vmcnt(16)
	v_mfma_f32_16x16x32_bf16 v[0:3], v[174:177], v[110:113], v[0:3]
	s_waitcnt vmcnt(15)
	v_mfma_f32_16x16x32_bf16 v[242:245], v[178:181], v[50:53], 0
	s_waitcnt vmcnt(14)
	v_mfma_f32_16x16x32_bf16 v[242:245], v[182:185], v[54:57], v[242:245]
	s_waitcnt vmcnt(13)
	v_mfma_f32_16x16x32_bf16 v[242:245], v[186:189], v[58:61], v[242:245]
	s_waitcnt vmcnt(12)
	v_mfma_f32_16x16x32_bf16 v[242:245], v[190:193], v[62:65], v[242:245]
	s_waitcnt vmcnt(11)
	v_mfma_f32_16x16x32_bf16 v[242:245], v[194:197], v[66:69], v[242:245]
	s_waitcnt vmcnt(10)
	v_mfma_f32_16x16x32_bf16 v[242:245], v[198:201], v[70:73], v[242:245]
	s_waitcnt vmcnt(9)
	v_mfma_f32_16x16x32_bf16 v[242:245], v[202:205], v[74:77], v[242:245]
	s_waitcnt vmcnt(8)
	v_mfma_f32_16x16x32_bf16 v[242:245], v[206:209], v[78:81], v[242:245]
	s_waitcnt vmcnt(7)
	v_mfma_f32_16x16x32_bf16 v[242:245], v[210:213], v[82:85], v[242:245]
	s_waitcnt vmcnt(6)
	v_mfma_f32_16x16x32_bf16 v[242:245], v[214:217], v[86:89], v[242:245]
	s_waitcnt vmcnt(5)
	v_mfma_f32_16x16x32_bf16 v[242:245], v[218:221], v[90:93], v[242:245]
	s_waitcnt vmcnt(4)
	v_mfma_f32_16x16x32_bf16 v[242:245], v[222:225], v[94:97], v[242:245]
	s_waitcnt vmcnt(3)
	v_mfma_f32_16x16x32_bf16 v[242:245], v[226:229], v[98:101], v[242:245]
	s_waitcnt vmcnt(2)
	v_mfma_f32_16x16x32_bf16 v[242:245], v[230:233], v[102:105], v[242:245]
	s_waitcnt vmcnt(1)
	v_mfma_f32_16x16x32_bf16 v[242:245], v[234:237], v[106:109], v[242:245]
	s_waitcnt vmcnt(0)
	v_mfma_f32_16x16x32_bf16 v[242:245], v[238:241], v[110:113], v[242:245]
	ds_write_b128 v4, v[0:3]
	s_lshl_b32 s2, s40, 1
	s_and_b32 s2, s2, 62
	s_and_b64 vcc, exec, s[0:1]
	s_mov_b64 s[24:25], -1
	s_nop 7
	ds_write_b128 v4, v[242:245] offset:8192
	s_waitcnt lgkmcnt(0)
	s_barrier
; __device__ __forceinline__ f32x4 unpack4(u32x2 w) { return (f32x4){bflo(w.x), bfhi(w.x), bflo(w.y), bfhi(w.y)}; }
; __device__ __forceinline__ int lane_fresh() { int l; asm volatile("v_mbcnt_lo_u32_b32 %0, -1, 0\n\tv_mbcnt_hi_u32_b32 %0, -1, %0" : "=v"(l)); return l; }
; __device__ __forceinline__ void phaseG(const Params& p, const int wv, const int rep, unsigned* bar, const bool fused) {
;     ...
;     if (!fused) {
;       if (wv < 2) {
;         const int lane_e = lane_fresh(), fr = lane_e & 15, fq = lane_e >> 4;
;         const int row = TP + mt * 16 + fr, col = (nt0 + wv) * 16 + fq * 4;
;         const size_t o = (size_t)row * 1024 + col;
;         *(f32x4*)(p.out + O_Y + o) = skreduce(wv) + unpack4(*(const u32x2*)(H2 + o));
;       }
;     } else {
;       unsigned* last_l = (unsigned*)g_shm + 8192;
;       if (wv < 2) {
;         const int lane_e = lane_fresh(), fr = lane_e & 15, fq = lane_e >> 4;
;         const int row = TP + mt * 16 + fr, col = (nt0 + wv) * 16 + fq * 4;
;         const size_t o = (size_t)row * 1024 + col;
;         f32x4 v = skreduce(wv) + unpack4(*(const u32x2*)(H2 + o));
;         float* yo = p.out + O_Y + o;
; #pragma unroll
;         for (int e = 0; e < 4; ++e) __hip_atomic_store(yo + e, v[e], __ATOMIC_RELAXED, __HIP_MEMORY_SCOPE_AGENT);
	s_cbranch_vccnz .LBB0_1191
	s_and_b64 vcc, exec, s[4:5]
	s_cbranch_vccnz .LBB0_1190
	v_mbcnt_lo_u32_b32 v1, -1, 0
	v_mbcnt_hi_u32_b32 v1, -1, v1
	s_or_b32 s19, s2, s41
	v_and_or_b32 v0, v1, 15, s20
	v_ashrrev_i32_e32 v1, 2, v1
	v_and_b32_e32 v1, -4, v1
	v_lshl_add_u32 v2, s19, 4, v1
	v_ashrrev_i32_e32 v1, 31, v0
	v_lshlrev_b64 v[0:1], 10, v[0:1]
	v_ashrrev_i32_e32 v3, 31, v2
	v_lshl_add_u64 v[36:37], v[0:1], 0, v[2:3]
	v_lshl_add_u64 v[0:1], v[36:37], 1, s[8:9]
	v_mbcnt_lo_u32_b32 v2, -1, 0
	v_mbcnt_hi_u32_b32 v2, -1, v2
	global_load_dwordx2 v[38:39], v[0:1], off
	v_lshl_add_u32 v4, v2, 4, s34
	ds_read_b128 v[0:3], v4
	ds_read_b128 v[6:9], v4 offset:1024
	ds_read_b128 v[10:13], v4 offset:2048
	ds_read_b128 v[16:19], v4 offset:3072
	ds_read_b128 v[20:23], v4 offset:4096
	ds_read_b128 v[24:27], v4 offset:5120
	ds_read_b128 v[28:31], v4 offset:6144
	ds_read_b128 v[32:35], v4 offset:7168
	s_waitcnt lgkmcnt(7)
	v_pk_add_f32 v[2:3], v[2:3], 0 op_sel_hi:[1,0]
	v_pk_add_f32 v[0:1], v[0:1], 0 op_sel_hi:[1,0]
	s_waitcnt lgkmcnt(6)
	v_pk_add_f32 v[2:3], v[2:3], v[8:9]
	v_pk_add_f32 v[0:1], v[0:1], v[6:7]
	s_waitcnt lgkmcnt(5)
	v_pk_add_f32 v[2:3], v[2:3], v[12:13]
	v_pk_add_f32 v[0:1], v[0:1], v[10:11]
	s_waitcnt lgkmcnt(4)
	v_pk_add_f32 v[2:3], v[2:3], v[18:19]
	v_pk_add_f32 v[0:1], v[0:1], v[16:17]
	s_waitcnt lgkmcnt(3)
	v_pk_add_f32 v[2:3], v[2:3], v[22:23]
	v_pk_add_f32 v[0:1], v[0:1], v[20:21]
	s_waitcnt lgkmcnt(2)
	v_pk_add_f32 v[2:3], v[2:3], v[26:27]
	v_pk_add_f32 v[0:1], v[0:1], v[24:25]
	s_waitcnt lgkmcnt(1)
	v_pk_add_f32 v[2:3], v[2:3], v[30:31]
	v_pk_add_f32 v[0:1], v[0:1], v[28:29]
	s_waitcnt lgkmcnt(0)
	v_pk_add_f32 v[2:3], v[2:3], v[34:35]
	v_pk_add_f32 v[0:1], v[0:1], v[32:33]
	s_waitcnt vmcnt(0)
	v_lshlrev_b32_e32 v6, 16, v38
	v_and_b32_e32 v7, 0xffff0000, v38
	v_lshlrev_b32_e32 v8, 16, v39
	v_and_b32_e32 v9, 0xffff0000, v39
	v_pk_add_f32 v[0:1], v[0:1], v[6:7]
	v_pk_add_f32 v[2:3], v[2:3], v[8:9]
	v_lshl_add_u64 v[6:7], v[36:37], 2, s[48:49]
	global_store_dwordx4 v[6:7], v[0:3], off sc1
